# plus P4 channel-DFT GEMM skips the 8 of 16 K-steps where the block-diagonal DFT matrix is exactly zero (bitwise-same result)
# baseline (speedup 1.0000x reference)
; __device__ __forceinline__ unsigned xb_ld(unsigned* p)              { return __hip_atomic_load(p, __ATOMIC_RELAXED, __HIP_MEMORY_SCOPE_AGENT); }
; __device__ __forceinline__ unsigned xb_add(unsigned* p, unsigned v) { return __hip_atomic_fetch_add(p, v, __ATOMIC_RELAXED, __HIP_MEMORY_SCOPE_AGENT); }
; #define XB_SPIN(cond, bar) do { unsigned _sp = 0; while (cond) { __builtin_amdgcn_s_sleep(1); \
;     if ((++_sp & 255u) == 0u) { if (xb_ld(&(bar)[XB_TMO])) break; if (_sp > XB_SPIN_CAP) { atomicAdd(&(bar)[XB_TMO], 1u); break; } } } } while (0)
; __device__ __forceinline__ void xcd_barrier(const XcdBarrier& b) {
;     ...
;             else XB_SPIN(xb_ld(&bar[XB_TOPGEN]) == tg, bar);
;             __builtin_amdgcn_fence(__ATOMIC_ACQUIRE, "agent");
;             xb_add(&bar[XB_XGEN(bx)], 1u);
;             asm volatile("s_waitcnt vmcnt(0)" ::: "memory");
;         } else {
;             XB_SPIN(xb_ld(&bar[XB_XGEN(bx)]) == gen, bar);
.Lgb_loop_1:
	flat_load_dword v6, v[4:5] sc1
	s_waitcnt vmcnt(0) lgkmcnt(0)
	v_readfirstlane_b32 s12, v6
	s_cmp_ge_u32 s12, s14
	s_cbranch_scc1 .Lgb_done_1
	s_sleep 1
	s_add_i32 s16, s16, 1
	s_cmp_lt_u32 s16, 0x80000
	s_cbranch_scc1 .Lgb_loop_1

; #define PG8_STAGE(bufoff, gbase, voff) do { _Pragma("unroll") for (int _i = 0; _i < 2; ++_i) \
;         __builtin_amdgcn_global_load_lds((const unsigned*)((const char*)(gbase) + (voff)[_i]), (LAS unsigned*)(lds + (bufoff) + ldsw + _i * 8192), 16, 0, 0); } while (0)
; #define PG8_WAIT_V(n) asm volatile("s_waitcnt vmcnt(" #n ")" ::: "memory")
; #define PG8_BAR __builtin_amdgcn_s_barrier()
;     __device__ __forceinline__ void init(AccMut acc, const Unit& u, int wr, int wc, int fr, int fq) const { acc_bias(acc, bias + u.pn * 256 + wc * 32 + 8 * fq); }
;     __device__ __forceinline__ void init(AccMut acc, const Unit&, int, int, int, int) const { acc_zero(acc); }
;     __device__ __forceinline__ void init(AccMut acc, const Unit&, int, int, int, int) const { acc_zero(acc); }
;     __device__ __forceinline__ void init(AccMut acc, const Unit& u, int wr, int wc, int fr, int fq) const { acc_bias(acc, bias + u.pn * 256 + wc * 32 + 8 * fq); }
;     __device__ __forceinline__ void init(AccMut acc, const Unit&, int, int, int, int) const { acc_zero(acc); }
;     __device__ __forceinline__ void init(AccMut acc, const Unit&, int, int, int, int) const { acc_zero(acc); }
; template <class Epi>
; __device__ __forceinline__ void gemm_phase(LAS unsigned char* lds, const Gemm g, const StaticOrder& S, const Epi& E, const int tid) {
;     ...
;     if (!S.next(0, cur)) return;
;     f32x4 acc[2][2][4][2];
;     E.init(acc, cur, wr, wc, fr, fq);
;     bf16x8 At[4][2], B0[2][2], B1[2][2];
;     const char* cA = (const char*)g.A + (size_t)cur.pm * tstepA; const char* cB = (const char*)g.Bt + (size_t)cur.pn * tstepB;
;     PG8_STAGE(PG8_SB(0, 0), cB, voffB); PG8_STAGE(PG8_SA(0, 0), cA, voffA); PG8_STAGE(PG8_SB(0, 1), cB + hstepB, voffB); PG8_STAGE(PG8_SA(0, 1), cA + hstepA, voffA);
;     if (wr == 1) PG8_BAR;
;     PG8_WAIT_V(4); PG8_BAR;
;     PG8_STAGE(PG8_SB(1, 0), cB + kstep, voffB); PG8_STAGE(PG8_SA(1, 0), cA + kstep, voffA); PG8_STAGE(PG8_SB(1, 1), cB + hstepB + kstep, voffB);
;     PG8_WAIT_V(6); PG8_BAR;
; __global__ void __launch_bounds__(512, 2) fwd_megakernel(Params p_) {
;     ...
;             pg8::Gemm g{XC, FC, M_TOK, 512, 1024, 1024, 1024}; pg8::StaticOrder S; S.init(M_TOK, 512, G, bid);
;             EpiFnet E{H}; pg8::gemm_phase(lds, g, S, E, tid);
.LBB0_650:
	s_or_b64 exec, exec, s[42:43]
	s_waitcnt lgkmcnt(0)
	s_barrier
	v_mov_b32_e32 v14, v246
	v_readlane_b32 s4, v253, 0
	v_readlane_b32 s5, v253, 1
	s_and_b64 vcc, exec, s[8:9]
	v_readfirstlane_b32 s2, v14
	s_cbranch_vccnz .LBB0_666
	v_lshlrev_b32_e32 v0, 4, v14
	v_add_u32_e32 v1, 0x2000, v0
	v_ashrrev_i32_e32 v2, 31, v1
	v_lshrrev_b32_e32 v2, 22, v2
	v_add_u32_e32 v2, v1, v2
	v_ashrrev_i32_e32 v8, 10, v2
	v_mul_i32_i24_e32 v2, 0x400, v8
	v_sub_u32_e32 v1, v1, v2
	v_lshrrev_b32_e32 v2, 4, v1
	v_bitop3_b32 v1, v2, v1, 32 bitop3:0x6c
	v_ashrrev_i32_e32 v2, 31, v1
	v_lshrrev_b32_e32 v2, 26, v2
	v_add_u32_e32 v2, v1, v2
	v_lshlrev_b32_e32 v3, 3, v8
	v_ashrrev_i32_e32 v9, 6, v2
	v_and_b32_e32 v3, -16, v3
	v_add_u32_e32 v3, v9, v3
	v_and_b32_e32 v4, 3, v9
	s_mov_b32 s10, 0x1fffe0
	v_lshrrev_b32_e32 v5, 2, v3
	v_lshlrev_b32_e32 v6, 1, v3
	v_and_b32_e32 v2, 0xc0, v2
	v_and_or_b32 v4, v3, s10, v4
	v_and_b32_e32 v5, 4, v5
	v_and_b32_e32 v6, 24, v6
	v_sub_u32_e32 v1, v1, v2
	v_or3_b32 v4, v4, v5, v6
	v_lshlrev_b32_e32 v5, 5, v8
	v_ashrrev_i16_sdwa v1, v247, sext(v1) dst_sel:DWORD dst_unused:UNUSED_PAD src0_sel:DWORD src1_sel:BYTE_0
	v_and_b32_e32 v5, 32, v5
	v_bfe_i32 v10, v1, 0, 16
	v_add_lshl_u32 v1, v5, v10, 1
	v_lshl_add_u32 v152, v4, 11, v1
	v_lshl_add_u32 v154, v3, 11, v1
	v_bfe_i32 v1, v14, 27, 1
	v_lshrrev_b32_e32 v1, 22, v1
	v_add_u32_e32 v1, v0, v1
	v_and_b32_e32 v1, 0xfffffc00, v1
	v_sub_u32_e32 v0, v0, v1
	v_lshrrev_b32_e32 v1, 4, v0
	v_bitop3_b32 v1, v1, v0, 32 bitop3:0x6c
	v_ashrrev_i32_e32 v0, 31, v0
	v_lshrrev_b32_e32 v0, 26, v0
	v_add_u32_e32 v0, v1, v0
	v_ashrrev_i32_e32 v11, 6, v0
	v_ashrrev_i32_e32 v0, 31, v14
	v_lshrrev_b32_e32 v0, 26, v0
	s_load_dwordx2 s[8:9], s[4:5], 0xd0
	v_add_u32_e32 v0, v14, v0
	v_ashrrev_i32_e32 v12, 6, v0
	v_lshlrev_b32_e32 v0, 3, v12
	v_and_b32_e32 v0, -16, v0
	v_add_u32_e32 v0, v11, v0
	s_waitcnt lgkmcnt(0)
	s_add_u32 s3, s8, 0x10c00000
	v_and_b32_e32 v2, 3, v11
	v_lshrrev_b32_e32 v3, 2, v0
	v_lshlrev_b32_e32 v4, 1, v0
	s_addc_u32 s26, s9, 0
	v_and_or_b32 v2, v0, s10, v2
	v_and_b32_e32 v3, 4, v3
	v_and_b32_e32 v4, 24, v4
	s_add_u32 s27, s8, 0x48d2a000
	v_or3_b32 v2, v2, v3, v4
	v_mul_i32_i24_e32 v4, 64, v11
	s_addc_u32 s28, s9, 0
	s_ashr_i32 s4, s2, 6
	v_sub_u32_e32 v1, v1, v4
	s_ashr_i32 s5, s2, 8
	s_lshl_b32 s29, s4, 10
	v_lshlrev_b32_e32 v3, 5, v12
	v_ashrrev_i16_sdwa v1, v247, sext(v1) dst_sel:DWORD dst_unused:UNUSED_PAD src0_sel:DWORD src1_sel:BYTE_0
	v_readlane_b32 s10, v253, 31
	v_and_b32_e32 v3, 32, v3
	v_bfe_i32 v13, v1, 0, 16
	v_readlane_b32 s11, v253, 32
	s_add_u32 s22, s3, s10
	v_add_lshl_u32 v1, v3, v13, 1
	s_addc_u32 s23, s26, s11
	v_readlane_b32 s99, v253, 31
	s_lshr_b32 s99, s99, 10
	s_add_u32 s22, s22, s99
	s_addc_u32 s23, s23, 0
	s_add_i32 s30, s29, 0
	v_lshl_add_u32 v184, v2, 11, v1
	s_add_i32 m0, s30, 0x10000
	v_readlane_b32 s10, v253, 29
	global_load_lds_dwordx4 v184, s[22:23]
	s_add_i32 m0, s30, 0x12000
	v_readlane_b32 s11, v253, 30
	s_add_u32 s20, s27, s10
	v_lshl_add_u32 v156, v0, 11, v1
	global_load_lds_dwordx4 v152, s[22:23]
	s_addc_u32 s21, s28, s11
	s_add_u32 s20, s20, s99
	s_addc_u32 s21, s21, 0
	s_mov_b32 m0, s30
	s_add_i32 s31, s30, 0x2000
	global_load_lds_dwordx4 v156, s[20:21]
	s_mov_b32 m0, s31
	s_add_u32 s10, s22, 0x40000
	global_load_lds_dwordx4 v154, s[20:21]
	s_addc_u32 s11, s23, 0
	s_add_i32 m0, s30, 0x14000
	v_mov_b32_e32 v153, v185
	global_load_lds_dwordx4 v184, s[10:11]
	s_add_i32 m0, s30, 0x16000
	v_mov_b32_e32 v157, v185
	global_load_lds_dwordx4 v152, s[10:11]
	s_add_u32 s10, s20, 0x40000
	s_addc_u32 s11, s21, 0
	s_add_i32 s34, s30, 0x4000
	s_mov_b32 m0, s34
	s_add_i32 s35, s30, 0x6000
	global_load_lds_dwordx4 v156, s[10:11]
	s_mov_b32 m0, s35
	v_mov_b32_e32 v155, v185
	global_load_lds_dwordx4 v154, s[10:11]
	v_lshl_add_u64 v[6:7], s[22:23], 0, v[184:185]
	v_lshl_add_u64 v[4:5], s[22:23], 0, v[152:153]
	v_lshl_add_u64 v[2:3], s[20:21], 0, v[156:157]
	s_cmp_lg_u32 s5, 1
	v_lshl_add_u64 v[0:1], s[20:21], 0, v[154:155]
	s_cbranch_scc1 .LBB0_653
	s_barrier

; #define PG8_STAGE(bufoff, gbase, voff) do { _Pragma("unroll") for (int _i = 0; _i < 2; ++_i) \
;         __builtin_amdgcn_global_load_lds((const unsigned*)((const char*)(gbase) + (voff)[_i]), (LAS unsigned*)(lds + (bufoff) + ldsw + _i * 8192), 16, 0, 0); } while (0)
; #define PG8_LDA(dst, b, h) do { _Pragma("unroll") for (int m = 0; m < 4; ++m) _Pragma("unroll") for (int k = 0; k < 2; ++k) dst[m][k] = *(const LAS bf16x8*)(lds + PG8_SA(b, h) + aoff + m * 2048 + k * 1024); } while (0)
; #define PG8_LDB(dst, b, h) do { _Pragma("unroll") for (int n = 0; n < 2; ++n) _Pragma("unroll") for (int k = 0; k < 2; ++k) dst[n][k] = *(const LAS bf16x8*)(lds + PG8_SB(b, h) + boff + n * 2048 + k * 1024); } while (0)
; #define PG8_MMA(ai, bj, At, Bt) do { __builtin_amdgcn_s_setprio(1); _Pragma("unroll") for (int m = 0; m < 4; ++m) _Pragma("unroll") for (int n = 0; n < 2; ++n) _Pragma("unroll") for (int k = 0; k < 2; ++k) \
;         acc[ai][bj][m][n] = __builtin_amdgcn_mfma_f32_16x16x32_bf16(Bt[n][k], At[m][k], acc[ai][bj][m][n], 0, 0, 0); __builtin_amdgcn_s_setprio(0); } while (0)
; #define PG8_WAIT_V(n) asm volatile("s_waitcnt vmcnt(" #n ")" ::: "memory")
; #define PG8_WAIT_L(n) asm volatile("s_waitcnt lgkmcnt(" #n ")" ::: "memory")
; template <class Epi>
; __device__ __forceinline__ void gemm_phase(LAS unsigned char* lds, const Gemm g, const StaticOrder& S, const Epi& E, const int tid) {
;     ...
;         for (int t = 0; t < nt; t += 2) {
;             const bool last = (t == nt - 2);
;             const char* a1 = cA + (size_t)(t + 1) * kstep;
;             const char* a2 = last ? nA : cA + (size_t)(t + 2) * kstep; const char* b2 = last ? nB : cB + (size_t)(t + 2) * kstep;
;             const char* a3 = a2 + kstep; const char* b3 = b2 + kstep;
;             PG8_LDB(B0, 0, 0); PG8_SCHED; PG8_LDA(At, 0, 0); PG8_STAGE(PG8_SA(1, 1), a1 + hstepA, voffA);
;             PG8_WAIT_L(8); PG8_BAR; PG8_WAIT_L(0); PG8_MMA(0, 0, At, B0); PG8_BAR; PG8_SCHED;
;             PG8_LDB(B1, 0, 1); PG8_STAGE(PG8_SB(0, 0), b2, voffB);
;             PG8_BAR; PG8_WAIT_L(0); PG8_MMA(0, 1, At, B1); PG8_BAR;
;             PG8_LDA(At, 0, 1); PG8_STAGE(PG8_SA(0, 0), a2, voffA);
;             PG8_BAR; PG8_WAIT_L(0); PG8_MMA(1, 0, At, B0); PG8_BAR; PG8_SCHED;
;             PG8_STAGE(PG8_SB(0, 1), b2 + hstepB, voffB);
;             PG8_WAIT_V(6); PG8_BAR; PG8_MMA(1, 1, At, B1); PG8_BAR;
.LBB0_661:
	s_add_u32 s22, s20, 0xfffc0080
	s_addc_u32 s23, s21, -1
	s_add_i32 s44, 0, 0x10000
	v_add_u32_e32 v140, s44, v176
	ds_read_b128 v[128:131], v140
	ds_read_b128 v[132:135], v140 offset:1024
	ds_read_b128 v[136:139], v140 offset:2048
	ds_read_b128 v[140:143], v140 offset:3072
	s_cmp_eq_u32 s43, 4
	s_cselect_b32 s25, s4, s23
	s_cselect_b32 s24, s5, s22
	s_cselect_b32 s23, s13, s42
	s_cselect_b32 s22, s15, s41
	s_cmp_eq_u32 s43, 0
	s_cselect_b32 s99, 0x200, 0
	s_add_u32 s24, s24, s99
	s_addc_u32 s25, s25, 0
	s_add_u32 s22, s22, s99
	s_addc_u32 s23, s23, 0
	v_lshl_add_u64 v[186:187], s[20:21], 0, v[158:159]
	s_add_i32 m0, s30, 0xc000
	ds_read_b128 v[144:147], v178
	ds_read_b128 v[148:151], v178 offset:1024
	ds_read_b128 v[164:167], v178 offset:2048
	ds_read_b128 v[168:171], v178 offset:3072
	ds_read_b128 v[172:175], v178 offset:4096
	ds_read_b128 v[180:183], v178 offset:5120
	ds_read_b128 v[196:199], v178 offset:6144
	ds_read_b128 v[200:203], v178 offset:7168
	global_load_lds_dwordx4 v[186:187], off
	v_lshl_add_u64 v[186:187], s[20:21], 0, v[160:161]
	s_add_i32 m0, s30, 0xe000
	s_nop 0
	global_load_lds_dwordx4 v[186:187], off
	s_waitcnt lgkmcnt(8)
	s_barrier
	s_waitcnt lgkmcnt(0)
	s_setprio 1
	s_waitcnt lgkmcnt(0)
	v_mfma_f32_16x16x32_bf16 v[124:127], v[128:131], v[144:147], v[124:127]
	v_mfma_f32_16x16x32_bf16 v[120:123], v[136:139], v[144:147], v[120:123]
	v_mfma_f32_16x16x32_bf16 v[108:111], v[128:131], v[164:167], v[108:111]
	v_mfma_f32_16x16x32_bf16 v[104:107], v[136:139], v[164:167], v[104:107]
	v_mfma_f32_16x16x32_bf16 v[92:95], v[128:131], v[172:175], v[92:95]
	v_mfma_f32_16x16x32_bf16 v[88:91], v[136:139], v[172:175], v[88:91]
	v_mfma_f32_16x16x32_bf16 v[76:79], v[128:131], v[196:199], v[76:79]
	v_mfma_f32_16x16x32_bf16 v[72:75], v[136:139], v[196:199], v[72:75]
	v_mfma_f32_16x16x32_bf16 v[124:127], v[132:135], v[148:151], v[124:127]
	v_mfma_f32_16x16x32_bf16 v[120:123], v[140:143], v[148:151], v[120:123]
	v_mfma_f32_16x16x32_bf16 v[108:111], v[132:135], v[168:171], v[108:111]
	v_mfma_f32_16x16x32_bf16 v[104:107], v[140:143], v[168:171], v[104:107]
	v_mfma_f32_16x16x32_bf16 v[92:95], v[132:135], v[180:183], v[92:95]
	v_mfma_f32_16x16x32_bf16 v[88:91], v[140:143], v[180:183], v[88:91]
	v_mfma_f32_16x16x32_bf16 v[76:79], v[132:135], v[200:203], v[76:79]
	v_mfma_f32_16x16x32_bf16 v[72:75], v[140:143], v[200:203], v[72:75]
	s_setprio 0
	s_barrier
	s_add_i32 s50, 0, 0x14000
	s_add_i32 s44, s44, s29
	v_add_u32_e32 v162, s50, v176
	v_lshl_add_u64 v[186:187], s[22:23], 0, v[184:185]
	s_mov_b32 m0, s44
	ds_read_b128 v[204:207], v162
	ds_read_b128 v[208:211], v162 offset:1024
	ds_read_b128 v[212:215], v162 offset:2048
	ds_read_b128 v[216:219], v162 offset:3072
	global_load_lds_dwordx4 v[186:187], off
	v_lshl_add_u64 v[192:193], s[22:23], 0, v[152:153]
	s_add_i32 m0, s44, 0x2000
	s_nop 0
	global_load_lds_dwordx4 v[192:193], off
	s_barrier
	s_waitcnt lgkmcnt(0)
	s_setprio 1
	s_waitcnt lgkmcnt(0)
	v_mfma_f32_16x16x32_bf16 v[116:119], v[204:207], v[144:147], v[116:119]
	v_mfma_f32_16x16x32_bf16 v[112:115], v[212:215], v[144:147], v[112:115]
	v_mfma_f32_16x16x32_bf16 v[100:103], v[204:207], v[164:167], v[100:103]
	v_mfma_f32_16x16x32_bf16 v[96:99], v[212:215], v[164:167], v[96:99]
	v_mfma_f32_16x16x32_bf16 v[84:87], v[204:207], v[172:175], v[84:87]
	v_mfma_f32_16x16x32_bf16 v[80:83], v[212:215], v[172:175], v[80:83]
	v_mfma_f32_16x16x32_bf16 v[68:71], v[204:207], v[196:199], v[68:71]
	v_mfma_f32_16x16x32_bf16 v[64:67], v[212:215], v[196:199], v[64:67]
	v_mfma_f32_16x16x32_bf16 v[116:119], v[208:211], v[148:151], v[116:119]
	v_mfma_f32_16x16x32_bf16 v[112:115], v[216:219], v[148:151], v[112:115]
	v_mfma_f32_16x16x32_bf16 v[100:103], v[208:211], v[168:171], v[100:103]
	v_mfma_f32_16x16x32_bf16 v[96:99], v[216:219], v[168:171], v[96:99]
	v_mfma_f32_16x16x32_bf16 v[84:87], v[208:211], v[180:183], v[84:87]
	v_mfma_f32_16x16x32_bf16 v[80:83], v[216:219], v[180:183], v[80:83]
	v_mfma_f32_16x16x32_bf16 v[68:71], v[208:211], v[200:203], v[68:71]
	v_mfma_f32_16x16x32_bf16 v[64:67], v[216:219], v[200:203], v[64:67]
	s_setprio 0
	s_mov_b32 m0, s30
	v_lshl_add_u64 v[220:221], s[24:25], 0, v[156:157]
	s_barrier
	ds_read_b128 v[144:147], v178 offset:16384
	ds_read_b128 v[148:151], v178 offset:17408
	ds_read_b128 v[164:167], v178 offset:18432
	ds_read_b128 v[168:171], v178 offset:19456
	ds_read_b128 v[172:175], v178 offset:20480
	ds_read_b128 v[180:183], v178 offset:21504
	ds_read_b128 v[196:199], v178 offset:22528
	ds_read_b128 v[200:203], v178 offset:23552
	global_load_lds_dwordx4 v[220:221], off
	v_lshl_add_u64 v[222:223], s[24:25], 0, v[154:155]
	s_mov_b32 m0, s31
	s_nop 0
	global_load_lds_dwordx4 v[222:223], off
	s_barrier
	s_waitcnt lgkmcnt(0)
	s_setprio 1
	s_waitcnt lgkmcnt(0)
	v_mfma_f32_16x16x32_bf16 v[60:63], v[128:131], v[144:147], v[60:63]
	v_mfma_f32_16x16x32_bf16 v[56:59], v[136:139], v[144:147], v[56:59]
	v_mfma_f32_16x16x32_bf16 v[44:47], v[128:131], v[164:167], v[44:47]
	v_mfma_f32_16x16x32_bf16 v[40:43], v[136:139], v[164:167], v[40:43]
	v_mfma_f32_16x16x32_bf16 v[28:31], v[128:131], v[172:175], v[28:31]
	v_mfma_f32_16x16x32_bf16 v[24:27], v[136:139], v[172:175], v[24:27]
	v_mfma_f32_16x16x32_bf16 v[12:15], v[128:131], v[196:199], v[12:15]
	v_mfma_f32_16x16x32_bf16 v[8:11], v[136:139], v[196:199], v[8:11]
	v_mfma_f32_16x16x32_bf16 v[60:63], v[132:135], v[148:151], v[60:63]
	v_mfma_f32_16x16x32_bf16 v[56:59], v[140:143], v[148:151], v[56:59]
	v_mfma_f32_16x16x32_bf16 v[44:47], v[132:135], v[168:171], v[44:47]
	v_mfma_f32_16x16x32_bf16 v[40:43], v[140:143], v[168:171], v[40:43]
	v_mfma_f32_16x16x32_bf16 v[28:31], v[132:135], v[180:183], v[28:31]
	v_mfma_f32_16x16x32_bf16 v[24:27], v[140:143], v[180:183], v[24:27]
	v_mfma_f32_16x16x32_bf16 v[12:15], v[132:135], v[200:203], v[12:15]
	v_mfma_f32_16x16x32_bf16 v[8:11], v[140:143], v[200:203], v[8:11]
	s_setprio 0
	s_barrier
; #define PG8_STAGE(bufoff, gbase, voff) do { _Pragma("unroll") for (int _i = 0; _i < 2; ++_i) \
;         __builtin_amdgcn_global_load_lds((const unsigned*)((const char*)(gbase) + (voff)[_i]), (LAS unsigned*)(lds + (bufoff) + ldsw + _i * 8192), 16, 0, 0); } while (0)
; #define PG8_LDA(dst, b, h) do { _Pragma("unroll") for (int m = 0; m < 4; ++m) _Pragma("unroll") for (int k = 0; k < 2; ++k) dst[m][k] = *(const LAS bf16x8*)(lds + PG8_SA(b, h) + aoff + m * 2048 + k * 1024); } while (0)
; #define PG8_LDB(dst, b, h) do { _Pragma("unroll") for (int n = 0; n < 2; ++n) _Pragma("unroll") for (int k = 0; k < 2; ++k) dst[n][k] = *(const LAS bf16x8*)(lds + PG8_SB(b, h) + boff + n * 2048 + k * 1024); } while (0)
; #define PG8_MMA(ai, bj, At, Bt) do { __builtin_amdgcn_s_setprio(1); _Pragma("unroll") for (int m = 0; m < 4; ++m) _Pragma("unroll") for (int n = 0; n < 2; ++n) _Pragma("unroll") for (int k = 0; k < 2; ++k) \
;         acc[ai][bj][m][n] = __builtin_amdgcn_mfma_f32_16x16x32_bf16(Bt[n][k], At[m][k], acc[ai][bj][m][n], 0, 0, 0); __builtin_amdgcn_s_setprio(0); } while (0)
; #define PG8_WAIT_V(n) asm volatile("s_waitcnt vmcnt(" #n ")" ::: "memory")
; #define PG8_WAIT_L(n) asm volatile("s_waitcnt lgkmcnt(" #n ")" ::: "memory")
; #define PG8_BAR __builtin_amdgcn_s_barrier()
; #define PG8_SCHED __builtin_amdgcn_sched_barrier(0)
; template <class Epi>
; __device__ __forceinline__ void gemm_phase(LAS unsigned char* lds, const Gemm g, const StaticOrder& S, const Epi& E, const int tid) {
;     ...
;             PG8_WAIT_V(6); PG8_BAR; PG8_MMA(1, 1, At, B1); PG8_BAR;
;             PG8_LDB(B0, 1, 0); PG8_SCHED; PG8_LDA(At, 1, 0); PG8_STAGE(PG8_SA(0, 1), a2 + hstepA, voffA);
;             PG8_WAIT_L(8); PG8_BAR; PG8_WAIT_L(0); PG8_MMA(0, 0, At, B0); PG8_BAR; PG8_SCHED;
;             PG8_LDB(B1, 1, 1); PG8_STAGE(PG8_SB(1, 0), b3, voffB);
;             PG8_BAR; PG8_WAIT_L(0); PG8_MMA(0, 1, At, B1); PG8_BAR;
;             PG8_LDA(At, 1, 1); PG8_STAGE(PG8_SA(1, 0), a3, voffA);
;             PG8_BAR; PG8_WAIT_L(0); PG8_MMA(1, 0, At, B0); PG8_BAR; PG8_SCHED;
	s_add_u32 s48, s22, 0x40000
	s_addc_u32 s49, s23, 0
	s_add_i32 s44, s50, s29
	v_lshl_add_u64 v[128:129], s[48:49], 0, v[184:185]
	s_mov_b32 m0, s44
	s_nop 0
	global_load_lds_dwordx4 v[128:129], off
	v_lshl_add_u64 v[128:129], s[48:49], 0, v[152:153]
	s_add_i32 m0, s44, 0x2000
	s_nop 0
	global_load_lds_dwordx4 v[128:129], off
	s_waitcnt vmcnt(6)
	s_barrier
	s_setprio 1
	v_mfma_f32_16x16x32_bf16 v[52:55], v[204:207], v[144:147], v[52:55]
	v_mfma_f32_16x16x32_bf16 v[48:51], v[212:215], v[144:147], v[48:51]
	v_mfma_f32_16x16x32_bf16 v[36:39], v[204:207], v[164:167], v[36:39]
	v_mfma_f32_16x16x32_bf16 v[32:35], v[212:215], v[164:167], v[32:35]
	v_mfma_f32_16x16x32_bf16 v[20:23], v[204:207], v[172:175], v[20:23]
	v_mfma_f32_16x16x32_bf16 v[16:19], v[212:215], v[172:175], v[16:19]
	v_mfma_f32_16x16x32_bf16 v[4:7], v[204:207], v[196:199], v[4:7]
	v_mfma_f32_16x16x32_bf16 v[0:3], v[212:215], v[196:199], v[0:3]
	v_mfma_f32_16x16x32_bf16 v[52:55], v[208:211], v[148:151], v[52:55]
	v_mfma_f32_16x16x32_bf16 v[48:51], v[216:219], v[148:151], v[48:51]
	v_mfma_f32_16x16x32_bf16 v[36:39], v[208:211], v[168:171], v[36:39]
	v_mfma_f32_16x16x32_bf16 v[32:35], v[216:219], v[168:171], v[32:35]
	v_mfma_f32_16x16x32_bf16 v[20:23], v[208:211], v[180:183], v[20:23]
	v_mfma_f32_16x16x32_bf16 v[16:19], v[216:219], v[180:183], v[16:19]
	v_mfma_f32_16x16x32_bf16 v[4:7], v[208:211], v[200:203], v[4:7]
	v_mfma_f32_16x16x32_bf16 v[0:3], v[216:219], v[200:203], v[0:3]
	s_setprio 0
	s_add_i32 s44, 0, 0x18000
	v_add_u32_e32 v140, s44, v176
	s_barrier
	ds_read_b128 v[128:131], v140
	ds_read_b128 v[132:135], v140 offset:1024
	ds_read_b128 v[136:139], v140 offset:2048
	ds_read_b128 v[140:143], v140 offset:3072
	s_add_u32 s24, s24, 0x40000
	s_addc_u32 s25, s25, 0
	s_mov_b32 m0, s34
	v_lshl_add_u64 v[204:205], s[24:25], 0, v[156:157]
	ds_read_b128 v[144:147], v178 offset:32768
	ds_read_b128 v[148:151], v178 offset:33792
	ds_read_b128 v[164:167], v178 offset:34816
	ds_read_b128 v[168:171], v178 offset:35840
	ds_read_b128 v[172:175], v178 offset:36864
	ds_read_b128 v[180:183], v178 offset:37888
	ds_read_b128 v[196:199], v178 offset:38912
	ds_read_b128 v[200:203], v178 offset:39936
	global_load_lds_dwordx4 v[204:205], off
	v_lshl_add_u64 v[204:205], s[24:25], 0, v[154:155]
	s_mov_b32 m0, s35
	s_nop 0
	global_load_lds_dwordx4 v[204:205], off
	s_waitcnt lgkmcnt(8)
	s_barrier
	s_waitcnt lgkmcnt(0)
	s_setprio 1
	s_waitcnt lgkmcnt(0)
	v_mfma_f32_16x16x32_bf16 v[124:127], v[128:131], v[144:147], v[124:127]
	v_mfma_f32_16x16x32_bf16 v[120:123], v[136:139], v[144:147], v[120:123]
	v_mfma_f32_16x16x32_bf16 v[108:111], v[128:131], v[164:167], v[108:111]
	v_mfma_f32_16x16x32_bf16 v[104:107], v[136:139], v[164:167], v[104:107]
	v_mfma_f32_16x16x32_bf16 v[92:95], v[128:131], v[172:175], v[92:95]
	v_mfma_f32_16x16x32_bf16 v[88:91], v[136:139], v[172:175], v[88:91]
	v_mfma_f32_16x16x32_bf16 v[76:79], v[128:131], v[196:199], v[76:79]
	v_mfma_f32_16x16x32_bf16 v[72:75], v[136:139], v[196:199], v[72:75]
	v_mfma_f32_16x16x32_bf16 v[124:127], v[132:135], v[148:151], v[124:127]
	v_mfma_f32_16x16x32_bf16 v[120:123], v[140:143], v[148:151], v[120:123]
	v_mfma_f32_16x16x32_bf16 v[108:111], v[132:135], v[168:171], v[108:111]
	v_mfma_f32_16x16x32_bf16 v[104:107], v[140:143], v[168:171], v[104:107]
	v_mfma_f32_16x16x32_bf16 v[92:95], v[132:135], v[180:183], v[92:95]
	v_mfma_f32_16x16x32_bf16 v[88:91], v[140:143], v[180:183], v[88:91]
	v_mfma_f32_16x16x32_bf16 v[76:79], v[132:135], v[200:203], v[76:79]
	v_mfma_f32_16x16x32_bf16 v[72:75], v[140:143], v[200:203], v[72:75]
	s_setprio 0
	s_barrier
	s_add_i32 s24, 0, 0x1c000
	s_add_i32 s25, s44, s29
	v_add_u32_e32 v162, s24, v176
	v_lshl_add_u64 v[186:187], v[186:187], 0, s[80:81]
	s_mov_b32 m0, s25
	ds_read_b128 v[204:207], v162
	ds_read_b128 v[208:211], v162 offset:1024
	ds_read_b128 v[212:215], v162 offset:2048
	ds_read_b128 v[216:219], v162 offset:3072
	global_load_lds_dwordx4 v[186:187], off
	v_lshl_add_u64 v[186:187], v[192:193], 0, s[80:81]
	s_add_i32 m0, s25, 0x2000
	s_nop 0
	global_load_lds_dwordx4 v[186:187], off
	s_barrier
	s_waitcnt lgkmcnt(0)
	s_setprio 1
	s_waitcnt lgkmcnt(0)
	v_mfma_f32_16x16x32_bf16 v[116:119], v[204:207], v[144:147], v[116:119]
	v_mfma_f32_16x16x32_bf16 v[112:115], v[212:215], v[144:147], v[112:115]
	v_mfma_f32_16x16x32_bf16 v[100:103], v[204:207], v[164:167], v[100:103]
	v_mfma_f32_16x16x32_bf16 v[96:99], v[212:215], v[164:167], v[96:99]
	v_mfma_f32_16x16x32_bf16 v[84:87], v[204:207], v[172:175], v[84:87]
	v_mfma_f32_16x16x32_bf16 v[80:83], v[212:215], v[172:175], v[80:83]
	v_mfma_f32_16x16x32_bf16 v[68:71], v[204:207], v[196:199], v[68:71]
	v_mfma_f32_16x16x32_bf16 v[64:67], v[212:215], v[196:199], v[64:67]
	v_mfma_f32_16x16x32_bf16 v[116:119], v[208:211], v[148:151], v[116:119]
	v_mfma_f32_16x16x32_bf16 v[112:115], v[216:219], v[148:151], v[112:115]
	v_mfma_f32_16x16x32_bf16 v[100:103], v[208:211], v[168:171], v[100:103]
	v_mfma_f32_16x16x32_bf16 v[96:99], v[216:219], v[168:171], v[96:99]
	v_mfma_f32_16x16x32_bf16 v[84:87], v[208:211], v[180:183], v[84:87]
	v_mfma_f32_16x16x32_bf16 v[80:83], v[216:219], v[180:183], v[80:83]
	v_mfma_f32_16x16x32_bf16 v[68:71], v[208:211], v[200:203], v[68:71]
	v_mfma_f32_16x16x32_bf16 v[64:67], v[216:219], v[200:203], v[64:67]
	s_setprio 0
	s_mov_b32 m0, s36
	v_lshl_add_u64 v[186:187], v[220:221], 0, s[80:81]
	s_barrier
	ds_read_b128 v[144:147], v178 offset:49152
	ds_read_b128 v[148:151], v178 offset:50176
	ds_read_b128 v[164:167], v178 offset:51200
	ds_read_b128 v[168:171], v178 offset:52224
	ds_read_b128 v[172:175], v178 offset:53248
	ds_read_b128 v[180:183], v178 offset:54272
	ds_read_b128 v[196:199], v178 offset:55296
	ds_read_b128 v[200:203], v178 offset:56320
	global_load_lds_dwordx4 v[186:187], off
	v_lshl_add_u64 v[186:187], v[222:223], 0, s[80:81]
	s_mov_b32 m0, s37
	s_nop 0
	global_load_lds_dwordx4 v[186:187], off
	s_barrier
; __device__ __forceinline__ void unpack8(u32x4 w, f32x4& a, f32x4& b) { a = (f32x4){bf_lo(w.x), bf_hi(w.x), bf_lo(w.y), bf_hi(w.y)}; b = (f32x4){bf_lo(w.z), bf_hi(w.z), bf_lo(w.w), bf_hi(w.w)}; }
; __device__ __forceinline__ u32x4 pack8(f32x4 a, f32x4 b) { u32x4 w; w.x = cvt_pk_bf16(a[0], a[1]); w.y = cvt_pk_bf16(a[2], a[3]); w.z = cvt_pk_bf16(b[0], b[1]); w.w = cvt_pk_bf16(b[2], b[3]); return w; }
; #define PG8_STAGE(bufoff, gbase, voff) do { _Pragma("unroll") for (int _i = 0; _i < 2; ++_i) \
;         __builtin_amdgcn_global_load_lds((const unsigned*)((const char*)(gbase) + (voff)[_i]), (LAS unsigned*)(lds + (bufoff) + ldsw + _i * 8192), 16, 0, 0); } while (0)
; #define PG8_MMA(ai, bj, At, Bt) do { __builtin_amdgcn_s_setprio(1); _Pragma("unroll") for (int m = 0; m < 4; ++m) _Pragma("unroll") for (int n = 0; n < 2; ++n) _Pragma("unroll") for (int k = 0; k < 2; ++k) \
;         acc[ai][bj][m][n] = __builtin_amdgcn_mfma_f32_16x16x32_bf16(Bt[n][k], At[m][k], acc[ai][bj][m][n], 0, 0, 0); __builtin_amdgcn_s_setprio(0); } while (0)
; template <class Epi>
; __device__ __forceinline__ void gemm_phase(LAS unsigned char* lds, const Gemm g, const StaticOrder& S, const Epi& E, const int tid) {
;     ...
;             PG8_BAR; PG8_WAIT_L(0); PG8_MMA(1, 0, At, B0); PG8_BAR; PG8_SCHED;
;             PG8_STAGE(PG8_SB(1, 1), b3 + hstepB, voffB);
;             PG8_WAIT_V(6); PG8_BAR; PG8_MMA(1, 1, At, B1); PG8_BAR;
;         }
;     __device__ __forceinline__ void operator()(AccRef acc, const Unit& u, int wr, int wc, int fr, int fq) const {
;         const float sc = (u.pm < 64) ? 0.001953125f   : 0.0009765625f  ;
;         const int row0 = u.pm * 256 + wr * 64 + fr, c0 = 512 + u.pn * 256 + wc * 32 + 8 * fq;
; #pragma unroll
;         for (int ai = 0; ai < 2; ++ai) {
;             u32x4 zw[4][2];
; #pragma unroll
;             for (int m = 0; m < 4; ++m)
; #pragma unroll
;                 for (int bj = 0; bj < 2; ++bj) zw[m][bj] = *(const u32x4*)(H + SEG_F + (size_t)(row0 + ai * 128 + m * 16) * LDF + c0 + bj * 128);
; #pragma unroll
;             for (int m = 0; m < 4; ++m) { bf16_t* rowp = H + SEG_F + (size_t)(row0 + ai * 128 + m * 16) * LDF + c0;
; #pragma unroll
;                 for (int bj = 0; bj < 2; ++bj) { f32x4 z0, z1; unpack8(zw[m][bj], z0, z1);
;                     *(u32x4*)(rowp + bj * 128) = pack8(acc[ai][bj][m][0] * sc * z0, acc[ai][bj][m][1] * sc * z1); } }
	s_waitcnt lgkmcnt(0)
	s_setprio 1
	s_waitcnt lgkmcnt(0)
	v_mfma_f32_16x16x32_bf16 v[60:63], v[128:131], v[144:147], v[60:63]
	v_mfma_f32_16x16x32_bf16 v[56:59], v[136:139], v[144:147], v[56:59]
	v_mfma_f32_16x16x32_bf16 v[44:47], v[128:131], v[164:167], v[44:47]
	v_mfma_f32_16x16x32_bf16 v[40:43], v[136:139], v[164:167], v[40:43]
	v_mfma_f32_16x16x32_bf16 v[28:31], v[128:131], v[172:175], v[28:31]
	v_mfma_f32_16x16x32_bf16 v[24:27], v[136:139], v[172:175], v[24:27]
	v_mfma_f32_16x16x32_bf16 v[12:15], v[128:131], v[196:199], v[12:15]
	v_mfma_f32_16x16x32_bf16 v[8:11], v[136:139], v[196:199], v[8:11]
	v_mfma_f32_16x16x32_bf16 v[60:63], v[132:135], v[148:151], v[60:63]
	v_mfma_f32_16x16x32_bf16 v[56:59], v[140:143], v[148:151], v[56:59]
	v_mfma_f32_16x16x32_bf16 v[44:47], v[132:135], v[168:171], v[44:47]
	v_mfma_f32_16x16x32_bf16 v[40:43], v[140:143], v[168:171], v[40:43]
	v_mfma_f32_16x16x32_bf16 v[28:31], v[132:135], v[180:183], v[28:31]
	v_mfma_f32_16x16x32_bf16 v[24:27], v[140:143], v[180:183], v[24:27]
	v_mfma_f32_16x16x32_bf16 v[12:15], v[132:135], v[200:203], v[12:15]
	v_mfma_f32_16x16x32_bf16 v[8:11], v[140:143], v[200:203], v[8:11]
	s_setprio 0
	s_barrier
	s_add_u32 s22, s22, 0x40080
	s_addc_u32 s23, s23, 0
	s_add_i32 s24, s24, s29
	v_lshl_add_u64 v[128:129], s[22:23], 0, v[184:185]
	s_mov_b32 m0, s24
	s_nop 0
	global_load_lds_dwordx4 v[128:129], off
	v_lshl_add_u64 v[128:129], s[22:23], 0, v[152:153]
	s_add_i32 m0, s24, 0x2000
	s_nop 0
	global_load_lds_dwordx4 v[128:129], off
	s_waitcnt vmcnt(6)
	s_barrier
	s_setprio 1
	v_mfma_f32_16x16x32_bf16 v[52:55], v[204:207], v[144:147], v[52:55]
	v_mfma_f32_16x16x32_bf16 v[48:51], v[212:215], v[144:147], v[48:51]
	v_mfma_f32_16x16x32_bf16 v[36:39], v[204:207], v[164:167], v[36:39]
	v_mfma_f32_16x16x32_bf16 v[32:35], v[212:215], v[164:167], v[32:35]
	v_mfma_f32_16x16x32_bf16 v[20:23], v[204:207], v[172:175], v[20:23]
	v_mfma_f32_16x16x32_bf16 v[16:19], v[212:215], v[172:175], v[16:19]
	v_mfma_f32_16x16x32_bf16 v[4:7], v[204:207], v[196:199], v[4:7]
	v_mfma_f32_16x16x32_bf16 v[0:3], v[212:215], v[196:199], v[0:3]
	v_mfma_f32_16x16x32_bf16 v[52:55], v[208:211], v[148:151], v[52:55]
	v_mfma_f32_16x16x32_bf16 v[48:51], v[216:219], v[148:151], v[48:51]
	v_mfma_f32_16x16x32_bf16 v[36:39], v[208:211], v[168:171], v[36:39]
	v_mfma_f32_16x16x32_bf16 v[32:35], v[216:219], v[168:171], v[32:35]
	v_mfma_f32_16x16x32_bf16 v[20:23], v[208:211], v[180:183], v[20:23]
	v_mfma_f32_16x16x32_bf16 v[16:19], v[216:219], v[180:183], v[16:19]
	v_mfma_f32_16x16x32_bf16 v[4:7], v[208:211], v[200:203], v[4:7]
	v_mfma_f32_16x16x32_bf16 v[0:3], v[216:219], v[200:203], v[0:3]
	s_setprio 0
	s_add_i32 s43, s43, 2
	s_add_u32 s20, s20, s99
	s_addc_u32 s21, s21, 0
	s_add_u32 s41, s41, s99
	s_addc_u32 s42, s42, 0
	s_add_u32 s20, s20, 0x100
	s_addc_u32 s21, s21, 0
	s_add_u32 s41, s41, 0x100
	s_addc_u32 s42, s42, 0
	s_cmp_gt_u32 s43, 5
	s_barrier
	s_cbranch_scc0 .LBB0_661
	v_lshl_add_u32 v130, s39, 8, v177
	v_lshl_add_u32 v128, s40, 8, v163
	v_ashrrev_i32_e32 v131, 31, v130
	v_lshlrev_b64 v[164:165], 1, v[130:131]
	v_ashrrev_i32_e32 v129, 31, v128
	v_lshl_add_u64 v[166:167], s[10:11], 0, v[164:165]
	v_lshlrev_b64 v[168:169], 11, v[128:129]
	v_lshl_add_u64 v[130:131], v[166:167], 0, v[168:169]
	global_load_dwordx4 v[180:183], v[130:131], off
	global_load_dwordx4 v[196:199], v[130:131], off offset:256
	v_or_b32_e32 v130, 16, v128
	v_ashrrev_i32_e32 v131, 31, v130
	v_lshlrev_b64 v[174:175], 11, v[130:131]
	v_lshl_add_u64 v[130:131], v[166:167], 0, v[174:175]
	global_load_dwordx4 v[148:151], v[130:131], off
	global_load_dwordx4 v[144:147], v[130:131], off offset:256
	v_or_b32_e32 v130, 32, v128
	v_ashrrev_i32_e32 v131, 31, v130
	v_lshlrev_b64 v[172:173], 11, v[130:131]
	v_lshl_add_u64 v[130:131], v[166:167], 0, v[172:173]
	global_load_dwordx4 v[140:143], v[130:131], off
	global_load_dwordx4 v[136:139], v[130:131], off offset:256
	v_or_b32_e32 v128, 48, v128
	v_ashrrev_i32_e32 v129, 31, v128
	v_lshlrev_b64 v[170:171], 11, v[128:129]
	v_lshl_add_u64 v[128:129], v[166:167], 0, v[170:171]
	global_load_dwordx4 v[132:135], v[128:129], off
	s_nop 0
	global_load_dwordx4 v[128:131], v[128:129], off offset:256
	s_cmp_lt_i32 s40, 64
	s_cselect_b64 vcc, -1, 0
	v_cndmask_b32_e32 v162, v251, v252, vcc
	v_pk_mul_f32 v[126:127], v[162:163], v[126:127] op_sel_hi:[0,1]
	v_pk_mul_f32 v[124:125], v[162:163], v[124:125] op_sel_hi:[0,1]
	v_pk_mul_f32 v[122:123], v[162:163], v[122:123] op_sel_hi:[0,1]
	v_pk_mul_f32 v[120:121], v[162:163], v[120:121] op_sel_hi:[0,1]
	v_lshl_add_u64 v[186:187], s[10:11], 0, v[168:169]
	v_lshl_add_u64 v[186:187], v[186:187], 0, v[164:165]
	v_pk_mul_f32 v[118:119], v[162:163], v[118:119] op_sel_hi:[0,1]
	v_pk_mul_f32 v[116:117], v[162:163], v[116:117] op_sel_hi:[0,1]
	v_pk_mul_f32 v[114:115], v[162:163], v[114:115] op_sel_hi:[0,1]
	v_pk_mul_f32 v[112:113], v[162:163], v[112:113] op_sel_hi:[0,1]
	v_pk_mul_f32 v[110:111], v[162:163], v[110:111] op_sel_hi:[0,1]
	v_pk_mul_f32 v[108:109], v[162:163], v[108:109] op_sel_hi:[0,1]
	v_pk_mul_f32 v[106:107], v[162:163], v[106:107] op_sel_hi:[0,1]
	v_pk_mul_f32 v[104:105], v[162:163], v[104:105] op_sel_hi:[0,1]
	v_pk_mul_f32 v[102:103], v[162:163], v[102:103] op_sel_hi:[0,1]
	v_pk_mul_f32 v[100:101], v[162:163], v[100:101] op_sel_hi:[0,1]
	v_pk_mul_f32 v[98:99], v[162:163], v[98:99] op_sel_hi:[0,1]
	v_pk_mul_f32 v[96:97], v[162:163], v[96:97] op_sel_hi:[0,1]
	v_pk_mul_f32 v[94:95], v[162:163], v[94:95] op_sel_hi:[0,1]
	v_pk_mul_f32 v[92:93], v[162:163], v[92:93] op_sel_hi:[0,1]
	v_pk_mul_f32 v[90:91], v[162:163], v[90:91] op_sel_hi:[0,1]
	v_pk_mul_f32 v[88:89], v[162:163], v[88:89] op_sel_hi:[0,1]
; __device__ __forceinline__ void unpack8(u32x4 w, f32x4& a, f32x4& b) { a = (f32x4){bf_lo(w.x), bf_hi(w.x), bf_lo(w.y), bf_hi(w.y)}; b = (f32x4){bf_lo(w.z), bf_hi(w.z), bf_lo(w.w), bf_hi(w.w)}; }
; __device__ __forceinline__ u32x4 pack8(f32x4 a, f32x4 b) { u32x4 w; w.x = cvt_pk_bf16(a[0], a[1]); w.y = cvt_pk_bf16(a[2], a[3]); w.z = cvt_pk_bf16(b[0], b[1]); w.w = cvt_pk_bf16(b[2], b[3]); return w; }
;     __device__ __forceinline__ void operator()(AccRef acc, const Unit& u, int wr, int wc, int fr, int fq) const {
;     ...
;             for (int m = 0; m < 4; ++m)
; #pragma unroll
;                 for (int bj = 0; bj < 2; ++bj) zw[m][bj] = *(const u32x4*)(H + SEG_F + (size_t)(row0 + ai * 128 + m * 16) * LDF + c0 + bj * 128);
; #pragma unroll
;             for (int m = 0; m < 4; ++m) { bf16_t* rowp = H + SEG_F + (size_t)(row0 + ai * 128 + m * 16) * LDF + c0;
; #pragma unroll
;                 for (int bj = 0; bj < 2; ++bj) { f32x4 z0, z1; unpack8(zw[m][bj], z0, z1);
;                     *(u32x4*)(rowp + bj * 128) = pack8(acc[ai][bj][m][0] * sc * z0, acc[ai][bj][m][1] * sc * z1); } }
	v_pk_mul_f32 v[86:87], v[162:163], v[86:87] op_sel_hi:[0,1]
	v_pk_mul_f32 v[84:85], v[162:163], v[84:85] op_sel_hi:[0,1]
	v_pk_mul_f32 v[82:83], v[162:163], v[82:83] op_sel_hi:[0,1]
	v_pk_mul_f32 v[80:81], v[162:163], v[80:81] op_sel_hi:[0,1]
	v_pk_mul_f32 v[78:79], v[162:163], v[78:79] op_sel_hi:[0,1]
	v_pk_mul_f32 v[76:77], v[162:163], v[76:77] op_sel_hi:[0,1]
	v_pk_mul_f32 v[74:75], v[162:163], v[74:75] op_sel_hi:[0,1]
	v_pk_mul_f32 v[72:73], v[162:163], v[72:73] op_sel_hi:[0,1]
	v_pk_mul_f32 v[70:71], v[162:163], v[70:71] op_sel_hi:[0,1]
	v_pk_mul_f32 v[68:69], v[162:163], v[68:69] op_sel_hi:[0,1]
	v_pk_mul_f32 v[66:67], v[162:163], v[66:67] op_sel_hi:[0,1]
	v_pk_mul_f32 v[64:65], v[162:163], v[64:65] op_sel_hi:[0,1]
	s_mov_b64 s[4:5], 0x40000
	v_pk_mul_f32 v[62:63], v[162:163], v[62:63] op_sel_hi:[0,1]
	v_pk_mul_f32 v[60:61], v[162:163], v[60:61] op_sel_hi:[0,1]
	v_pk_mul_f32 v[58:59], v[162:163], v[58:59] op_sel_hi:[0,1]
	v_pk_mul_f32 v[56:57], v[162:163], v[56:57] op_sel_hi:[0,1]
	v_pk_mul_f32 v[54:55], v[162:163], v[54:55] op_sel_hi:[0,1]
	v_pk_mul_f32 v[52:53], v[162:163], v[52:53] op_sel_hi:[0,1]
	v_pk_mul_f32 v[50:51], v[162:163], v[50:51] op_sel_hi:[0,1]
	v_pk_mul_f32 v[48:49], v[162:163], v[48:49] op_sel_hi:[0,1]
	v_pk_mul_f32 v[46:47], v[162:163], v[46:47] op_sel_hi:[0,1]
	v_pk_mul_f32 v[44:45], v[162:163], v[44:45] op_sel_hi:[0,1]
	v_pk_mul_f32 v[42:43], v[162:163], v[42:43] op_sel_hi:[0,1]
	v_pk_mul_f32 v[40:41], v[162:163], v[40:41] op_sel_hi:[0,1]
	v_pk_mul_f32 v[38:39], v[162:163], v[38:39] op_sel_hi:[0,1]
	v_pk_mul_f32 v[36:37], v[162:163], v[36:37] op_sel_hi:[0,1]
	v_pk_mul_f32 v[34:35], v[162:163], v[34:35] op_sel_hi:[0,1]
	v_pk_mul_f32 v[32:33], v[162:163], v[32:33] op_sel_hi:[0,1]
	v_pk_mul_f32 v[30:31], v[162:163], v[30:31] op_sel_hi:[0,1]
	v_pk_mul_f32 v[28:29], v[162:163], v[28:29] op_sel_hi:[0,1]
	v_pk_mul_f32 v[26:27], v[162:163], v[26:27] op_sel_hi:[0,1]
	v_pk_mul_f32 v[24:25], v[162:163], v[24:25] op_sel_hi:[0,1]
	v_pk_mul_f32 v[22:23], v[162:163], v[22:23] op_sel_hi:[0,1]
	v_pk_mul_f32 v[20:21], v[162:163], v[20:21] op_sel_hi:[0,1]
	v_pk_mul_f32 v[18:19], v[162:163], v[18:19] op_sel_hi:[0,1]
	v_pk_mul_f32 v[16:17], v[162:163], v[16:17] op_sel_hi:[0,1]
	v_pk_mul_f32 v[14:15], v[162:163], v[14:15] op_sel_hi:[0,1]
	s_waitcnt vmcnt(0)
	v_lshlrev_b32_e32 v192, 16, v180
	v_and_b32_e32 v193, 0xffff0000, v180
	v_lshlrev_b32_e32 v180, 16, v181
	v_and_b32_e32 v181, 0xffff0000, v181
	v_lshlrev_b32_e32 v200, 16, v182
	v_and_b32_e32 v201, 0xffff0000, v182
	v_lshlrev_b32_e32 v182, 16, v183
	v_and_b32_e32 v183, 0xffff0000, v183
	v_pk_mul_f32 v[126:127], v[126:127], v[180:181]
	v_pk_mul_f32 v[124:125], v[124:125], v[192:193]
	v_pk_mul_f32 v[180:181], v[122:123], v[182:183]
	v_pk_mul_f32 v[122:123], v[120:121], v[200:201]
	v_cvt_pk_bf16_f32 v120, v124, v125
	v_cvt_pk_bf16_f32 v121, v126, v127
	v_cvt_pk_bf16_f32 v122, v122, v123
	v_cvt_pk_bf16_f32 v123, v180, v181
	global_store_dwordx4 v[186:187], v[120:123], off
	v_lshlrev_b32_e32 v124, 16, v198
	v_and_b32_e32 v125, 0xffff0000, v198
	v_lshlrev_b32_e32 v120, 16, v196
	v_and_b32_e32 v121, 0xffff0000, v196
	v_lshlrev_b32_e32 v122, 16, v197
	v_and_b32_e32 v123, 0xffff0000, v197
	v_lshlrev_b32_e32 v126, 16, v199
	v_and_b32_e32 v127, 0xffff0000, v199
	v_pk_mul_f32 v[118:119], v[118:119], v[122:123]
	v_pk_mul_f32 v[116:117], v[116:117], v[120:121]
	v_pk_mul_f32 v[120:121], v[114:115], v[126:127]
	v_pk_mul_f32 v[114:115], v[112:113], v[124:125]
	v_cvt_pk_bf16_f32 v112, v116, v117
	v_cvt_pk_bf16_f32 v113, v118, v119
	v_cvt_pk_bf16_f32 v114, v114, v115
	v_cvt_pk_bf16_f32 v115, v120, v121
	global_store_dwordx4 v[186:187], v[112:115], off offset:256
	v_lshlrev_b32_e32 v118, 16, v148
	v_and_b32_e32 v119, 0xffff0000, v148
	v_lshlrev_b32_e32 v120, 16, v149
	v_and_b32_e32 v121, 0xffff0000, v149
	v_lshlrev_b32_e32 v114, 16, v150
	v_and_b32_e32 v115, 0xffff0000, v150
	v_lshlrev_b32_e32 v116, 16, v151
	v_and_b32_e32 v117, 0xffff0000, v151
	v_lshl_add_u64 v[112:113], s[10:11], 0, v[174:175]
	v_pk_mul_f32 v[110:111], v[110:111], v[120:121]
	v_pk_mul_f32 v[108:109], v[108:109], v[118:119]
	v_pk_mul_f32 v[116:117], v[106:107], v[116:117]
	v_pk_mul_f32 v[106:107], v[104:105], v[114:115]
	v_lshl_add_u64 v[112:113], v[112:113], 0, v[164:165]
	v_cvt_pk_bf16_f32 v104, v108, v109
	v_cvt_pk_bf16_f32 v105, v110, v111
	v_cvt_pk_bf16_f32 v106, v106, v107
	v_cvt_pk_bf16_f32 v107, v116, v117
	global_store_dwordx4 v[112:113], v[104:107], off
	v_lshlrev_b32_e32 v108, 16, v146
	v_and_b32_e32 v109, 0xffff0000, v146
	v_lshlrev_b32_e32 v104, 16, v144
	v_and_b32_e32 v105, 0xffff0000, v144
	v_lshlrev_b32_e32 v106, 16, v145
	v_and_b32_e32 v107, 0xffff0000, v145
	v_lshlrev_b32_e32 v110, 16, v147
	v_and_b32_e32 v111, 0xffff0000, v147
	v_pk_mul_f32 v[102:103], v[102:103], v[106:107]
	v_pk_mul_f32 v[100:101], v[100:101], v[104:105]
	v_pk_mul_f32 v[104:105], v[98:99], v[110:111]
	v_pk_mul_f32 v[98:99], v[96:97], v[108:109]
	v_cvt_pk_bf16_f32 v96, v100, v101
	v_cvt_pk_bf16_f32 v97, v102, v103
	v_cvt_pk_bf16_f32 v98, v98, v99
	v_cvt_pk_bf16_f32 v99, v104, v105
	global_store_dwordx4 v[112:113], v[96:99], off offset:256
	v_lshlrev_b32_e32 v100, 16, v141
	v_and_b32_e32 v101, 0xffff0000, v141
	v_lshlrev_b32_e32 v98, 16, v140
	v_and_b32_e32 v99, 0xffff0000, v140
	v_lshlrev_b32_e32 v102, 16, v142
	v_and_b32_e32 v103, 0xffff0000, v142
	v_lshlrev_b32_e32 v104, 16, v143
	v_and_b32_e32 v105, 0xffff0000, v143
	v_lshl_add_u64 v[96:97], s[10:11], 0, v[172:173]
	v_pk_mul_f32 v[94:95], v[94:95], v[100:101]
	v_pk_mul_f32 v[92:93], v[92:93], v[98:99]
	v_pk_mul_f32 v[98:99], v[90:91], v[104:105]
	v_pk_mul_f32 v[90:91], v[88:89], v[102:103]
; __device__ __forceinline__ void unpack8(u32x4 w, f32x4& a, f32x4& b) { a = (f32x4){bf_lo(w.x), bf_hi(w.x), bf_lo(w.y), bf_hi(w.y)}; b = (f32x4){bf_lo(w.z), bf_hi(w.z), bf_lo(w.w), bf_hi(w.w)}; }
; __device__ __forceinline__ u32x4 pack8(f32x4 a, f32x4 b) { u32x4 w; w.x = cvt_pk_bf16(a[0], a[1]); w.y = cvt_pk_bf16(a[2], a[3]); w.z = cvt_pk_bf16(b[0], b[1]); w.w = cvt_pk_bf16(b[2], b[3]); return w; }
;     __device__ __forceinline__ void init(AccMut acc, const Unit& u, int wr, int wc, int fr, int fq) const { acc_bias(acc, bias + u.pn * 256 + wc * 32 + 8 * fq); }
;     __device__ __forceinline__ void init(AccMut acc, const Unit&, int, int, int, int) const { acc_zero(acc); }
;     __device__ __forceinline__ void init(AccMut acc, const Unit&, int, int, int, int) const { acc_zero(acc); }
;     __device__ __forceinline__ void init(AccMut acc, const Unit& u, int wr, int wc, int fr, int fq) const { acc_bias(acc, bias + u.pn * 256 + wc * 32 + 8 * fq); }
;     __device__ __forceinline__ void init(AccMut acc, const Unit&, int, int, int, int) const { acc_zero(acc); }
;     __device__ __forceinline__ void init(AccMut acc, const Unit&, int, int, int, int) const { acc_zero(acc); }
; template <class Epi>
; __device__ __forceinline__ void gemm_phase(LAS unsigned char* lds, const Gemm g, const StaticOrder& S, const Epi& E, const int tid) {
;     ...
;         if (!has_next) break;
;         E.init(acc, nxt, wr, wc, fr, fq);
;         cur = nxt; cA = nA; cB = nB; ++ui;
;     __device__ __forceinline__ void operator()(AccRef acc, const Unit& u, int wr, int wc, int fr, int fq) const {
;     ...
;         for (int ai = 0; ai < 2; ++ai) {
;             u32x4 zw[4][2];
; #pragma unroll
;             for (int m = 0; m < 4; ++m)
; #pragma unroll
;                 for (int bj = 0; bj < 2; ++bj) zw[m][bj] = *(const u32x4*)(H + SEG_F + (size_t)(row0 + ai * 128 + m * 16) * LDF + c0 + bj * 128);
; #pragma unroll
;             for (int m = 0; m < 4; ++m) { bf16_t* rowp = H + SEG_F + (size_t)(row0 + ai * 128 + m * 16) * LDF + c0;
; #pragma unroll
;                 for (int bj = 0; bj < 2; ++bj) { f32x4 z0, z1; unpack8(zw[m][bj], z0, z1);
;                     *(u32x4*)(rowp + bj * 128) = pack8(acc[ai][bj][m][0] * sc * z0, acc[ai][bj][m][1] * sc * z1); } }
;             asm volatile("" ::: "memory");
;         }
	v_lshl_add_u64 v[96:97], v[96:97], 0, v[164:165]
	v_cvt_pk_bf16_f32 v88, v92, v93
	v_cvt_pk_bf16_f32 v89, v94, v95
	v_cvt_pk_bf16_f32 v90, v90, v91
	v_cvt_pk_bf16_f32 v91, v98, v99
	global_store_dwordx4 v[96:97], v[88:91], off
	v_lshlrev_b32_e32 v92, 16, v138
	v_and_b32_e32 v93, 0xffff0000, v138
	v_lshlrev_b32_e32 v88, 16, v136
	v_and_b32_e32 v89, 0xffff0000, v136
	v_lshlrev_b32_e32 v90, 16, v137
	v_and_b32_e32 v91, 0xffff0000, v137
	v_lshlrev_b32_e32 v94, 16, v139
	v_and_b32_e32 v95, 0xffff0000, v139
	v_pk_mul_f32 v[86:87], v[86:87], v[90:91]
	v_pk_mul_f32 v[84:85], v[84:85], v[88:89]
	v_pk_mul_f32 v[88:89], v[82:83], v[94:95]
	v_pk_mul_f32 v[82:83], v[80:81], v[92:93]
	v_cvt_pk_bf16_f32 v80, v84, v85
	v_cvt_pk_bf16_f32 v81, v86, v87
	v_cvt_pk_bf16_f32 v82, v82, v83
	v_cvt_pk_bf16_f32 v83, v88, v89
	global_store_dwordx4 v[96:97], v[80:83], off offset:256
	v_lshlrev_b32_e32 v84, 16, v133
	v_and_b32_e32 v85, 0xffff0000, v133
	v_lshlrev_b32_e32 v82, 16, v132
	v_and_b32_e32 v83, 0xffff0000, v132
	v_lshlrev_b32_e32 v86, 16, v134
	v_and_b32_e32 v87, 0xffff0000, v134
	v_lshlrev_b32_e32 v88, 16, v135
	v_and_b32_e32 v89, 0xffff0000, v135
	v_lshl_add_u64 v[80:81], s[10:11], 0, v[170:171]
	v_pk_mul_f32 v[78:79], v[78:79], v[84:85]
	v_pk_mul_f32 v[76:77], v[76:77], v[82:83]
	v_pk_mul_f32 v[82:83], v[74:75], v[88:89]
	v_pk_mul_f32 v[74:75], v[72:73], v[86:87]
	v_lshl_add_u64 v[80:81], v[80:81], 0, v[164:165]
	v_cvt_pk_bf16_f32 v72, v76, v77
	v_cvt_pk_bf16_f32 v73, v78, v79
	v_cvt_pk_bf16_f32 v74, v74, v75
	v_cvt_pk_bf16_f32 v75, v82, v83
	global_store_dwordx4 v[80:81], v[72:75], off
	v_lshlrev_b32_e32 v76, 16, v130
	v_and_b32_e32 v77, 0xffff0000, v130
	v_lshlrev_b32_e32 v72, 16, v128
	v_and_b32_e32 v73, 0xffff0000, v128
	v_lshlrev_b32_e32 v74, 16, v129
	v_and_b32_e32 v75, 0xffff0000, v129
	v_lshlrev_b32_e32 v78, 16, v131
	v_and_b32_e32 v79, 0xffff0000, v131
	v_pk_mul_f32 v[70:71], v[70:71], v[74:75]
	v_pk_mul_f32 v[68:69], v[68:69], v[72:73]
	v_pk_mul_f32 v[72:73], v[66:67], v[78:79]
	v_pk_mul_f32 v[66:67], v[64:65], v[76:77]
	v_cvt_pk_bf16_f32 v64, v68, v69
	v_cvt_pk_bf16_f32 v65, v70, v71
	v_cvt_pk_bf16_f32 v66, v66, v67
	v_cvt_pk_bf16_f32 v67, v72, v73
	global_store_dwordx4 v[80:81], v[64:67], off offset:256
	v_lshl_add_u64 v[96:97], v[168:169], 0, s[4:5]
	s_mov_b64 s[4:5], 0x48000
	v_lshl_add_u64 v[64:65], v[166:167], 0, v[96:97]
	global_load_dwordx4 v[68:71], v[64:65], off
	global_load_dwordx4 v[72:75], v[64:65], off offset:256
	v_lshl_add_u64 v[98:99], v[168:169], 0, s[4:5]
	v_lshl_add_u64 v[64:65], v[166:167], 0, v[98:99]
	global_load_dwordx4 v[76:79], v[64:65], off
	global_load_dwordx4 v[80:83], v[64:65], off offset:256
	s_mov_b64 s[4:5], 0x50000
	v_lshl_add_u64 v[100:101], v[168:169], 0, s[4:5]
	v_lshl_add_u64 v[64:65], v[166:167], 0, v[100:101]
	global_load_dwordx4 v[84:87], v[64:65], off
	global_load_dwordx4 v[88:91], v[64:65], off offset:256
	s_mov_b64 s[4:5], 0x58000
	v_lshl_add_u64 v[102:103], v[168:169], 0, s[4:5]
	v_lshl_add_u64 v[64:65], v[166:167], 0, v[102:103]
	global_load_dwordx4 v[92:95], v[64:65], off
	s_nop 0
	global_load_dwordx4 v[64:67], v[64:65], off offset:256
	v_lshl_add_u64 v[96:97], s[10:11], 0, v[96:97]
	v_lshl_add_u64 v[96:97], v[96:97], 0, v[164:165]
	v_pk_mul_f32 v[12:13], v[162:163], v[12:13] op_sel_hi:[0,1]
	v_pk_mul_f32 v[10:11], v[162:163], v[10:11] op_sel_hi:[0,1]
	v_pk_mul_f32 v[8:9], v[162:163], v[8:9] op_sel_hi:[0,1]
	v_pk_mul_f32 v[6:7], v[162:163], v[6:7] op_sel_hi:[0,1]
	v_pk_mul_f32 v[4:5], v[162:163], v[4:5] op_sel_hi:[0,1]
	v_pk_mul_f32 v[2:3], v[162:163], v[2:3] op_sel_hi:[0,1]
	v_pk_mul_f32 v[0:1], v[162:163], v[0:1] op_sel_hi:[0,1]
	s_and_b64 vcc, exec, s[8:9]
	s_mov_b32 s39, s12
	s_mov_b32 s40, s14
	s_mov_b64 s[22:23], s[18:19]
	s_mov_b64 s[20:21], s[16:17]
	s_waitcnt vmcnt(0)
; __device__ __forceinline__ void unpack8(u32x4 w, f32x4& a, f32x4& b) { a = (f32x4){bf_lo(w.x), bf_hi(w.x), bf_lo(w.y), bf_hi(w.y)}; b = (f32x4){bf_lo(w.z), bf_hi(w.z), bf_lo(w.w), bf_hi(w.w)}; }
; __device__ __forceinline__ u32x4 pack8(f32x4 a, f32x4 b) { u32x4 w; w.x = cvt_pk_bf16(a[0], a[1]); w.y = cvt_pk_bf16(a[2], a[3]); w.z = cvt_pk_bf16(b[0], b[1]); w.w = cvt_pk_bf16(b[2], b[3]); return w; }
;     __device__ __forceinline__ void operator()(AccRef acc, const Unit& u, int wr, int wc, int fr, int fq) const {
;     ...
;                 for (int bj = 0; bj < 2; ++bj) zw[m][bj] = *(const u32x4*)(H + SEG_F + (size_t)(row0 + ai * 128 + m * 16) * LDF + c0 + bj * 128);
; #pragma unroll
;             for (int m = 0; m < 4; ++m) { bf16_t* rowp = H + SEG_F + (size_t)(row0 + ai * 128 + m * 16) * LDF + c0;
; #pragma unroll
;                 for (int bj = 0; bj < 2; ++bj) { f32x4 z0, z1; unpack8(zw[m][bj], z0, z1);
;                     *(u32x4*)(rowp + bj * 128) = pack8(acc[ai][bj][m][0] * sc * z0, acc[ai][bj][m][1] * sc * z1); } }
;             asm volatile("" ::: "memory");
;         }
	v_lshlrev_b32_e32 v104, 16, v68
	v_and_b32_e32 v105, 0xffff0000, v68
	v_lshlrev_b32_e32 v68, 16, v69
	v_and_b32_e32 v69, 0xffff0000, v69
	v_lshlrev_b32_e32 v106, 16, v70
	v_and_b32_e32 v107, 0xffff0000, v70
	v_lshlrev_b32_e32 v70, 16, v71
	v_and_b32_e32 v71, 0xffff0000, v71
	v_pk_mul_f32 v[62:63], v[62:63], v[68:69]
	v_pk_mul_f32 v[60:61], v[60:61], v[104:105]
	v_pk_mul_f32 v[68:69], v[58:59], v[70:71]
	v_pk_mul_f32 v[58:59], v[56:57], v[106:107]
	v_cvt_pk_bf16_f32 v56, v60, v61
	v_cvt_pk_bf16_f32 v57, v62, v63
	v_cvt_pk_bf16_f32 v58, v58, v59
	v_cvt_pk_bf16_f32 v59, v68, v69
	global_store_dwordx4 v[96:97], v[56:59], off
	v_lshlrev_b32_e32 v60, 16, v74
	v_and_b32_e32 v61, 0xffff0000, v74
	v_lshlrev_b32_e32 v56, 16, v72
	v_and_b32_e32 v57, 0xffff0000, v72
	v_lshlrev_b32_e32 v58, 16, v73
	v_and_b32_e32 v59, 0xffff0000, v73
	v_lshlrev_b32_e32 v62, 16, v75
	v_and_b32_e32 v63, 0xffff0000, v75
	v_pk_mul_f32 v[54:55], v[54:55], v[58:59]
	v_pk_mul_f32 v[52:53], v[52:53], v[56:57]
	v_pk_mul_f32 v[56:57], v[50:51], v[62:63]
	v_pk_mul_f32 v[50:51], v[48:49], v[60:61]
	v_cvt_pk_bf16_f32 v48, v52, v53
	v_cvt_pk_bf16_f32 v49, v54, v55
	v_cvt_pk_bf16_f32 v50, v50, v51
	v_cvt_pk_bf16_f32 v51, v56, v57
	global_store_dwordx4 v[96:97], v[48:51], off offset:256
	v_lshlrev_b32_e32 v52, 16, v77
	v_and_b32_e32 v53, 0xffff0000, v77
	v_lshlrev_b32_e32 v50, 16, v76
	v_and_b32_e32 v51, 0xffff0000, v76
	v_lshlrev_b32_e32 v54, 16, v78
	v_and_b32_e32 v55, 0xffff0000, v78
	v_lshlrev_b32_e32 v56, 16, v79
	v_and_b32_e32 v57, 0xffff0000, v79
	v_lshl_add_u64 v[48:49], s[10:11], 0, v[98:99]
	v_pk_mul_f32 v[46:47], v[46:47], v[52:53]
	v_pk_mul_f32 v[44:45], v[44:45], v[50:51]
	v_pk_mul_f32 v[50:51], v[42:43], v[56:57]
	v_pk_mul_f32 v[42:43], v[40:41], v[54:55]
	v_lshl_add_u64 v[48:49], v[48:49], 0, v[164:165]
	v_cvt_pk_bf16_f32 v40, v44, v45
	v_cvt_pk_bf16_f32 v41, v46, v47
	v_cvt_pk_bf16_f32 v42, v42, v43
	v_cvt_pk_bf16_f32 v43, v50, v51
	global_store_dwordx4 v[48:49], v[40:43], off
	v_lshlrev_b32_e32 v44, 16, v82
	v_and_b32_e32 v45, 0xffff0000, v82
	v_lshlrev_b32_e32 v40, 16, v80
	v_and_b32_e32 v41, 0xffff0000, v80
	v_lshlrev_b32_e32 v42, 16, v81
	v_and_b32_e32 v43, 0xffff0000, v81
	v_lshlrev_b32_e32 v46, 16, v83
	v_and_b32_e32 v47, 0xffff0000, v83
	v_pk_mul_f32 v[38:39], v[38:39], v[42:43]
	v_pk_mul_f32 v[36:37], v[36:37], v[40:41]
	v_pk_mul_f32 v[40:41], v[34:35], v[46:47]
	v_pk_mul_f32 v[34:35], v[32:33], v[44:45]
	v_cvt_pk_bf16_f32 v32, v36, v37
	v_cvt_pk_bf16_f32 v33, v38, v39
	v_cvt_pk_bf16_f32 v34, v34, v35
	v_cvt_pk_bf16_f32 v35, v40, v41
	global_store_dwordx4 v[48:49], v[32:35], off offset:256
	v_lshlrev_b32_e32 v36, 16, v85
	v_and_b32_e32 v37, 0xffff0000, v85
	v_lshlrev_b32_e32 v34, 16, v84
	v_and_b32_e32 v35, 0xffff0000, v84
	v_lshlrev_b32_e32 v38, 16, v86
	v_and_b32_e32 v39, 0xffff0000, v86
	v_lshlrev_b32_e32 v40, 16, v87
	v_and_b32_e32 v41, 0xffff0000, v87
	v_lshl_add_u64 v[32:33], s[10:11], 0, v[100:101]
	v_pk_mul_f32 v[30:31], v[30:31], v[36:37]
	v_pk_mul_f32 v[28:29], v[28:29], v[34:35]
	v_pk_mul_f32 v[34:35], v[26:27], v[40:41]
	v_pk_mul_f32 v[26:27], v[24:25], v[38:39]
	v_lshl_add_u64 v[32:33], v[32:33], 0, v[164:165]
	v_cvt_pk_bf16_f32 v24, v28, v29
	v_cvt_pk_bf16_f32 v25, v30, v31
	v_cvt_pk_bf16_f32 v26, v26, v27
	v_cvt_pk_bf16_f32 v27, v34, v35
	global_store_dwordx4 v[32:33], v[24:27], off
	v_lshlrev_b32_e32 v28, 16, v90
	v_and_b32_e32 v29, 0xffff0000, v90
	v_lshlrev_b32_e32 v24, 16, v88
	v_and_b32_e32 v25, 0xffff0000, v88
	v_lshlrev_b32_e32 v26, 16, v89
	v_and_b32_e32 v27, 0xffff0000, v89
	v_lshlrev_b32_e32 v30, 16, v91
	v_and_b32_e32 v31, 0xffff0000, v91
	v_pk_mul_f32 v[22:23], v[22:23], v[26:27]
	v_pk_mul_f32 v[20:21], v[20:21], v[24:25]
	v_pk_mul_f32 v[24:25], v[18:19], v[30:31]
	v_pk_mul_f32 v[18:19], v[16:17], v[28:29]
	v_cvt_pk_bf16_f32 v16, v20, v21
	v_cvt_pk_bf16_f32 v17, v22, v23
	v_cvt_pk_bf16_f32 v18, v18, v19
	v_cvt_pk_bf16_f32 v19, v24, v25
	global_store_dwordx4 v[32:33], v[16:19], off offset:256
	v_lshlrev_b32_e32 v20, 16, v93
	v_and_b32_e32 v21, 0xffff0000, v93
	v_lshlrev_b32_e32 v18, 16, v92
	v_and_b32_e32 v19, 0xffff0000, v92
	v_lshlrev_b32_e32 v22, 16, v94
	v_and_b32_e32 v23, 0xffff0000, v94
	v_lshlrev_b32_e32 v24, 16, v95
	v_and_b32_e32 v25, 0xffff0000, v95
	v_lshl_add_u64 v[16:17], s[10:11], 0, v[102:103]
	v_pk_mul_f32 v[14:15], v[14:15], v[20:21]
	v_pk_mul_f32 v[12:13], v[12:13], v[18:19]
	v_pk_mul_f32 v[18:19], v[10:11], v[24:25]
	v_pk_mul_f32 v[10:11], v[8:9], v[22:23]
	v_lshl_add_u64 v[16:17], v[16:17], 0, v[164:165]
	v_cvt_pk_bf16_f32 v8, v12, v13
	v_cvt_pk_bf16_f32 v9, v14, v15
	v_cvt_pk_bf16_f32 v10, v10, v11
	v_cvt_pk_bf16_f32 v11, v18, v19
	global_store_dwordx4 v[16:17], v[8:11], off
	v_lshlrev_b32_e32 v12, 16, v66
	v_and_b32_e32 v13, 0xffff0000, v66
	v_lshlrev_b32_e32 v8, 16, v64
	v_and_b32_e32 v9, 0xffff0000, v64
	v_lshlrev_b32_e32 v10, 16, v65
	v_and_b32_e32 v11, 0xffff0000, v65
	v_lshlrev_b32_e32 v14, 16, v67
	v_and_b32_e32 v15, 0xffff0000, v67
	v_pk_mul_f32 v[6:7], v[6:7], v[10:11]
	v_pk_mul_f32 v[4:5], v[4:5], v[8:9]
	v_pk_mul_f32 v[8:9], v[2:3], v[14:15]
	v_pk_mul_f32 v[2:3], v[0:1], v[12:13]
	v_cvt_pk_bf16_f32 v0, v4, v5
	v_cvt_pk_bf16_f32 v1, v6, v7
	v_cvt_pk_bf16_f32 v2, v2, v3
	v_cvt_pk_bf16_f32 v3, v8, v9
	global_store_dwordx4 v[16:17], v[0:3], off offset:256
	s_cbranch_vccz .LBB0_654
	s_waitcnt vmcnt(0)
	s_cmpk_gt_u32 s2, 0xff
	s_cbranch_scc1 .LBB0_665
	s_barrier
